# S tile 0 (block 0, always first in the ascending union list) is requested at the start of the work item into the even staging set; guarded by a check of list[0]
# baseline (speedup 1.0000x reference)
.LBB0_1929:
	s_or_b64 exec, exec, s[22:23]
	ds_write_b32 v175, v105 offset:8448
	ds_write_b32 v175, v105 offset:9472
	ds_write_b32 v175, v105 offset:10496
	ds_write_b32 v175, v105 offset:11520
	ds_write_b32 v175, v105 offset:12544
	ds_write_b32 v175, v105 offset:13568
	ds_write_b32 v175, v105 offset:14592
	ds_write_b32 v175, v105 offset:15616
	ds_write_b32 v175, v105 offset:16640
	s_lshl_b32 s20, s99, 1
	s_and_b32 s70, s20, -16
	s_sub_i32 s67, 0x1ff0, s70
	v_add_u32_e32 v132, s67, v103
	s_lshl_b32 s20, s99, 12
	s_and_b32 s54, s20, 0x6000
	s_mov_b32 s55, s39
	v_ashrrev_i32_e32 v133, 31, v132
	s_lshl_b32 s20, s99, 3
	v_lshl_add_u64 v[2:3], v[132:133], 0, s[54:55]
	s_and_b32 s55, s20, 8
	v_lshlrev_b64 v[4:5], 11, v[2:3]
	v_or_b32_e32 v6, s55, v102
	v_lshl_add_u64 v[4:5], s[42:43], 0, v[4:5]
	v_lshlrev_b32_e32 v104, 7, v6
	v_mad_u64_u32 v[6:7], s[20:21], v2, s49, v[124:125]
	v_lshl_add_u64 v[4:5], v[4:5], 0, v[104:105]
	v_mad_i32_i24 v7, v3, s49, v7
	s_lshl_b32 s20, s55, 2
	s_mov_b32 s21, s39
	v_lshl_add_u64 v[4:5], v[4:5], 0, v[122:123]
	v_lshl_add_u64 v[2:3], v[6:7], 0, s[20:21]
	global_load_dwordx4 v[66:69], v[4:5], off offset:32
	global_load_dwordx4 v[70:73], v[4:5], off offset:64
	global_load_dwordx4 v[74:77], v[4:5], off offset:96
	v_lshl_add_u64 v[130:131], v[2:3], 0, v[126:127]
	global_load_dwordx4 v[78:81], v[4:5], off
	global_load_dword v133, v[130:131], off
	global_load_dword v104, v[130:131], off offset:128
	s_and_b32 s20, s99, 7
	s_lshl_b32 s38, s20, 16
	s_lshr_b32 s20, s30, 4
	s_add_i32 s20, s20, 63
	s_lshr_b32 s20, s20, 6
	s_sub_i32 s28, 0, s20
	s_lshr_b32 s20, s67, 4
	s_and_b32 s71, s99, 7
	s_lshl_b32 s80, s71, 20
	v_readlane_b32 s76, v231, 14
	v_readlane_b32 s77, v231, 10
	s_add_u32 s76, s76, s80
	s_addc_u32 s77, s77, 0
	s_add_u32 s78, s52, s80
	s_addc_u32 s79, s53, 0
	v_add_u32_e32 v240, v128, v106
	global_load_dwordx4 v[240:243], v240, s[76:77]
	v_add_u32_e32 v244, v128, v106
	global_load_dwordx4 v[244:247], v244, s[78:79]
	v_add_u32_e32 v248, v128, v108
	global_load_dwordx4 v[248:251], v248, s[76:77]
	v_add_u32_e32 v252, v128, v108
	global_load_dwordx4 v[252:255], v252, s[78:79]
	s_add_i32 s20, s20, 63
	s_lshr_b32 s29, s20, 6
	s_lshl_b32 s30, s71, 16
	s_add_u32 s22, s26, s30
	s_addc_u32 s23, s27, 0
	s_cmpk_lg_i32 s70, 0x1ff0
	s_cselect_b64 s[24:25], -1, 0
	s_cmpk_eq_i32 s70, 0x1ff0
	v_mov_b32_e32 v54, 0
	s_cbranch_scc1 .LBB0_1942
	v_mov_b32_e32 v129, v105
	v_lshl_add_u64 v[2:3], s[22:23], 0, v[128:129]
	v_lshl_add_u64 v[4:5], v[2:3], 0, v[106:107]
	v_lshl_add_u64 v[6:7], v[2:3], 0, v[108:109]
	global_load_dwordx4 v[34:37], v[4:5], off
	global_load_dwordx4 v[38:41], v[6:7], off
	s_cmp_eq_u32 s29, 1
	s_waitcnt vmcnt(1)
	ds_write_b128 v153, v[34:37]
	s_waitcnt vmcnt(0)
	ds_write_b128 v155, v[38:41]
	s_cbranch_scc1 .LBB0_1932
	v_lshl_add_u64 v[2:3], v[2:3], 0, s[40:41]
	v_lshl_add_u64 v[4:5], v[2:3], 0, v[106:107]
	v_lshl_add_u64 v[2:3], v[2:3], 0, v[108:109]
	global_load_dwordx4 v[34:37], v[4:5], off
	global_load_dwordx4 v[38:41], v[2:3], off

.LBB0_2164:
	s_or_b64 exec, exec, s[20:21]
	v_add_u32_e32 v38, v34, v35
	v_bcnt_u32_b32 v37, v37, 0
	v_add_u32_e32 v38, v38, v36
	v_add_u32_e32 v150, v38, v37
	v_mul_f32_e32 v38, v133, v146
	v_cmp_eq_u32_e32 vcc, 0, v150
	v_pk_mul_f32 v[82:83], v[38:39], v[18:19] op_sel_hi:[0,1]
	v_add_u32_e32 v215, 0x9000, v214
	v_pk_mul_f32 v[84:85], v[38:39], v[20:21] op_sel_hi:[0,1]
	v_add_u32_e32 v216, 0x9008, v214
	v_pk_mul_f32 v[86:87], v[38:39], v[22:23] op_sel_hi:[0,1]
	v_add_u32_e32 v217, 0x9020, v214
	v_pk_mul_f32 v[88:89], v[38:39], v[24:25] op_sel_hi:[0,1]
	v_add_u32_e32 v218, 0x9028, v214
	v_pk_mul_f32 v[90:91], v[38:39], v[26:27] op_sel_hi:[0,1]
	v_add_u32_e32 v219, 0x9040, v214
	v_pk_mul_f32 v[92:93], v[38:39], v[28:29] op_sel_hi:[0,1]
	v_add_u32_e32 v220, 0x9048, v214
	v_pk_mul_f32 v[94:95], v[38:39], v[30:31] op_sel_hi:[0,1]
	v_add_u32_e32 v221, 0x9060, v214
	v_pk_mul_f32 v[96:97], v[38:39], v[32:33] op_sel_hi:[0,1]
	v_add_u32_e32 v222, 0x9068, v214
	v_pk_mul_f32 v[134:135], v[38:39], v[2:3] op_sel_hi:[0,1]
	v_add_u32_e32 v223, 0x9080, v214
	v_pk_mul_f32 v[136:137], v[38:39], v[4:5] op_sel_hi:[0,1]
	v_add_u32_e32 v224, 0x9088, v214
	v_pk_mul_f32 v[138:139], v[38:39], v[6:7] op_sel_hi:[0,1]
	v_add_u32_e32 v225, 0x90a0, v214
	v_pk_mul_f32 v[140:141], v[38:39], v[8:9] op_sel_hi:[0,1]
	v_add_u32_e32 v226, 0x90a8, v214
	v_pk_mul_f32 v[142:143], v[38:39], v[10:11] op_sel_hi:[0,1]
	v_add_u32_e32 v227, 0x90c0, v214
	v_pk_mul_f32 v[144:145], v[38:39], v[12:13] op_sel_hi:[0,1]
	v_add_u32_e32 v228, 0x90c8, v214
	v_pk_mul_f32 v[146:147], v[38:39], v[14:15] op_sel_hi:[0,1]
	v_add_u32_e32 v229, 0x90e0, v214
	v_pk_mul_f32 v[148:149], v[38:39], v[16:17] op_sel_hi:[0,1]
	v_add_u32_e32 v230, 0x90e8, v214
	s_and_b64 vcc, exec, vcc
	s_lshl_b32 s24, s71, 19
	s_waitcnt lgkmcnt(0)
	s_barrier
	ds_write2_b32 v215, v82, v83 offset1:1
	ds_write2_b32 v216, v84, v85 offset1:1
	ds_write2_b32 v217, v86, v87 offset1:1
	ds_write2_b32 v218, v88, v89 offset1:1
	ds_write2_b32 v219, v90, v91 offset1:1
	ds_write2_b32 v220, v92, v93 offset1:1
	ds_write2_b32 v221, v94, v95 offset1:1
	ds_write2_b32 v222, v96, v97 offset1:1
	ds_write2_b32 v223, v134, v135 offset1:1
	ds_write2_b32 v224, v136, v137 offset1:1
	ds_write2_b32 v225, v138, v139 offset1:1
	ds_write2_b32 v226, v140, v141 offset1:1
	ds_write2_b32 v227, v142, v143 offset1:1
	ds_write2_b32 v228, v144, v145 offset1:1
	ds_write2_b32 v229, v146, v147 offset1:1
	ds_write2_b32 v230, v148, v149 offset1:1
	s_cbranch_vccnz .LBB0_2181
	s_lshl_b32 s96, s66, 12
	s_and_b32 s96, s96, 0x6000
	s_lshl_b32 s95, s66, 3
	s_and_b32 s95, s95, 8
	s_sub_i32 s94, 0x1ff0, s70
	s_mov_b32 s98, 0x1000
	s_mov_b32 s99, 0
	v_and_b32_e32 v40, 15, v166
	v_bfe_u32 v41, v166, 4, 2
	v_lshrrev_b32_e32 v42, 6, v166
	v_lshlrev_b32_e32 v36, 4, v42
	v_and_b32_e32 v37, 63, v166
	v_readfirstlane_b32 s86, v36
	s_lshr_b32 s86, s86, 2
	s_lshl_b32 s87, 12, s86
	s_lshl_b32 s86, 3, s86
	v_lshlrev_b32_e32 v37, 2, v37
	v_add_u32_e32 v37, 0x11200, v37
	ds_read_b32 v133, v37 offset:256
	ds_read_b32 v148, v37 offset:512
	v_mul_u32_u24_e32 v234, 0x90, v40
	v_lshl_add_u32 v234, v41, 4, v234
	v_bfe_u32 v43, v166, 3, 1
	v_lshl_add_u32 v43, v42, 2, v43
	v_add_u32_e32 v236, s94, v43
	v_lshlrev_b32_e32 v44, 2, v41
	v_sub_u32_e32 v239, v236, v44
	v_lshl_add_u32 v45, v42, 5, v40
	v_mul_u32_u24_e32 v45, 0x41, v45
	v_lshl_add_u32 v45, v41, 2, v45
	v_lshlrev_b32_e32 v45, 2, v45
	v_add_u32_e32 v237, 0x9000, v45
	v_add_u32_e32 v238, 0x1040, v237
	v_add_u32_e32 v46, s96, v236
	v_mov_b32_e32 v47, 0
	v_lshlrev_b64 v[46:47], 11, v[46:47]
	v_lshl_add_u64 v[46:47], s[42:43], 0, v[46:47]
	v_and_b32_e32 v48, 7, v166
	v_or_b32_e32 v48, s95, v48
	v_lshlrev_b32_e32 v48, 7, v48
	v_lshl_add_u32 v48, v41, 4, v48
	v_mov_b32_e32 v49, 0
	v_lshl_add_u64 v[46:47], v[46:47], 0, v[48:49]
	global_load_dwordx4 v[66:69], v[46:47], off
	global_load_dwordx4 v[70:73], v[46:47], off offset:64
	v_lshl_add_u64 v[48:49], v[46:47], 0, s[98:99]
	global_load_dwordx4 v[74:77], v[48:49], off
	global_load_dwordx4 v[78:81], v[48:49], off offset:64
	v_mov_b32_e32 v235, 0
	v_add_u32_e32 v46, s96, v236
	v_mov_b32_e32 v47, 0xc0
	v_mad_u64_u32 v[38:39], s[98:99], v46, v47, v[124:125]
	v_and_b32_e32 v48, 7, v166
	v_or_b32_e32 v48, s95, v48
	v_lshlrev_b32_e32 v48, 2, v48
	v_mov_b32_e32 v49, 0
	v_lshl_add_u64 v[38:39], v[38:39], 0, v[48:49]
	global_load_dword v149, v[38:39], off offset:64
	global_load_dword v147, v[38:39], off offset:448
	s_lshl_b32 s22, s24, 1
	v_readlane_b32 s20, v231, 14
	s_add_u32 s20, s20, s22
	v_readlane_b32 s21, v231, 10
	s_addc_u32 s21, s21, 0
	s_add_u32 s22, s52, s22
	s_addc_u32 s23, s53, 0
	v_add_u32_e32 v134, v128, v106
	v_add_u32_e32 v135, v128, v108
	v_readfirstlane_b32 s101, v150
	s_mov_b32 s25, 0
	s_waitcnt lgkmcnt(0)
	v_readlane_b32 s32, v133, 0
	s_cmp_eq_u32 s32, 0
	s_cbranch_scc1 .Lsb16_t0ok
	s_and_b32 s38, s25, 63
	v_readlane_b32 s32, v133, s38
	v_readlane_b32 s38, v148, s38
	s_bitcmp1_b32 s25, 6
	s_cselect_b32 s32, s38, s32
	s_lshl_b32 s32, s32, 13
	s_add_u32 s28, s20, s32
	s_addc_u32 s29, s21, 0
	s_add_u32 s82, s22, s32
	s_addc_u32 s83, s23, 0
	global_load_dwordx4 v[240:243], v134, s[28:29]
	global_load_dwordx4 v[244:247], v134, s[82:83]
	global_load_dwordx4 v[248:251], v135, s[28:29]
	global_load_dwordx4 v[252:255], v135, s[82:83]
.Lsb16_t0ok:
	s_cmp_lt_u32 s101, 2
	s_cbranch_scc1 .Lsb16_pa
	s_mov_b32 s58, 1
	s_and_b32 s38, s58, 63
	v_readlane_b32 s32, v133, s38
	v_readlane_b32 s38, v148, s38
	s_bitcmp1_b32 s58, 6
	s_cselect_b32 s32, s38, s32
	s_lshl_b32 s32, s32, 13
	s_add_u32 s28, s20, s32
	s_addc_u32 s29, s21, 0
	s_add_u32 s82, s22, s32
	s_addc_u32 s83, s23, 0
	global_load_dwordx4 v[82:85], v134, s[28:29]
	global_load_dwordx4 v[86:89], v134, s[82:83]
	global_load_dwordx4 v[90:93], v135, s[28:29]
	global_load_dwordx4 v[94:97], v135, s[82:83]

.Lsb16_pb:
	ds_write_b128 v153, v[240:243]
	ds_write_b128 v153, v[244:247] offset:9216
	ds_write_b128 v155, v[248:251]
	ds_write_b128 v155, v[252:255] offset:9216
	s_cmp_lt_u32 s101, 3
	s_cbranch_scc1 .Lsb16_pc
	s_mov_b32 s58, 2
	s_and_b32 s38, s58, 63
	v_readlane_b32 s32, v133, s38
	v_readlane_b32 s38, v148, s38
	s_bitcmp1_b32 s58, 6
	s_cselect_b32 s32, s38, s32
	s_lshl_b32 s32, s32, 13
	s_add_u32 s28, s20, s32
	s_addc_u32 s29, s21, 0
	s_add_u32 s82, s22, s32
	s_addc_u32 s83, s23, 0
	global_load_dwordx4 v[240:243], v134, s[28:29]
	global_load_dwordx4 v[244:247], v134, s[82:83]
	global_load_dwordx4 v[248:251], v135, s[28:29]
	global_load_dwordx4 v[252:255], v135, s[82:83]

.Lsb16_wr_f_0:
	ds_write_b128 v153, v[82:85] offset:18432
	ds_write_b128 v153, v[86:89] offset:27648
	ds_write_b128 v155, v[90:93] offset:18432
	ds_write_b128 v155, v[94:97] offset:27648
	s_add_i32 s58, s25, 3
	s_cmp_ge_u32 s58, s101
	s_cbranch_scc1 .Lsb16_done_f_0
	s_and_b32 s38, s58, 63
	v_readlane_b32 s32, v133, s38
	v_readlane_b32 s38, v148, s38
	s_bitcmp1_b32 s58, 6
	s_cselect_b32 s32, s38, s32
	s_lshl_b32 s32, s32, 13
	s_add_u32 s28, s20, s32
	s_addc_u32 s29, s21, 0
	s_add_u32 s82, s22, s32
	s_addc_u32 s83, s23, 0
	global_load_dwordx4 v[82:85], v134, s[28:29]
	global_load_dwordx4 v[86:89], v134, s[82:83]
	global_load_dwordx4 v[90:93], v135, s[28:29]
	global_load_dwordx4 v[94:97], v135, s[82:83]
	s_branch .Lsb16_done_f_0

.Lsb16_wr_i_0:
	ds_write_b128 v153, v[82:85] offset:18432
	ds_write_b128 v153, v[86:89] offset:27648
	ds_write_b128 v155, v[90:93] offset:18432
	ds_write_b128 v155, v[94:97] offset:27648
	s_add_i32 s58, s25, 3
	s_cmp_ge_u32 s58, s101
	s_cbranch_scc1 .Lsb16_done_i_0
	s_and_b32 s38, s58, 63
	v_readlane_b32 s32, v133, s38
	v_readlane_b32 s38, v148, s38
	s_bitcmp1_b32 s58, 6
	s_cselect_b32 s32, s38, s32
	s_lshl_b32 s32, s32, 13
	s_add_u32 s28, s20, s32
	s_addc_u32 s29, s21, 0
	s_add_u32 s82, s22, s32
	s_addc_u32 s83, s23, 0
	global_load_dwordx4 v[82:85], v134, s[28:29]
	global_load_dwordx4 v[86:89], v134, s[82:83]
	global_load_dwordx4 v[90:93], v135, s[28:29]
	global_load_dwordx4 v[94:97], v135, s[82:83]

.Lsb16_wr_f_1:
	ds_write_b128 v153, v[240:243]
	ds_write_b128 v153, v[244:247] offset:9216
	ds_write_b128 v155, v[248:251]
	ds_write_b128 v155, v[252:255] offset:9216
	s_add_i32 s58, s25, 3
	s_cmp_ge_u32 s58, s101
	s_cbranch_scc1 .Lsb16_done_f_1
	s_and_b32 s38, s58, 63
	v_readlane_b32 s32, v133, s38
	v_readlane_b32 s38, v148, s38
	s_bitcmp1_b32 s58, 6
	s_cselect_b32 s32, s38, s32
	s_lshl_b32 s32, s32, 13
	s_add_u32 s28, s20, s32
	s_addc_u32 s29, s21, 0
	s_add_u32 s82, s22, s32
	s_addc_u32 s83, s23, 0
	global_load_dwordx4 v[240:243], v134, s[28:29]
	global_load_dwordx4 v[244:247], v134, s[82:83]
	global_load_dwordx4 v[248:251], v135, s[28:29]
	global_load_dwordx4 v[252:255], v135, s[82:83]
	s_branch .Lsb16_done_f_1

.Lsb16_wr_i_1:
	ds_write_b128 v153, v[240:243]
	ds_write_b128 v153, v[244:247] offset:9216
	ds_write_b128 v155, v[248:251]
	ds_write_b128 v155, v[252:255] offset:9216
	s_add_i32 s58, s25, 3
	s_cmp_ge_u32 s58, s101
	s_cbranch_scc1 .Lsb16_done_i_1
	s_and_b32 s38, s58, 63
	v_readlane_b32 s32, v133, s38
	v_readlane_b32 s38, v148, s38
	s_bitcmp1_b32 s58, 6
	s_cselect_b32 s32, s38, s32
	s_lshl_b32 s32, s32, 13
	s_add_u32 s28, s20, s32
	s_addc_u32 s29, s21, 0
	s_add_u32 s82, s22, s32
	s_addc_u32 s83, s23, 0
	global_load_dwordx4 v[240:243], v134, s[28:29]
	global_load_dwordx4 v[244:247], v134, s[82:83]
	global_load_dwordx4 v[248:251], v135, s[28:29]
	global_load_dwordx4 v[252:255], v135, s[82:83]

.LBB0_2180:
	s_sub_i32 s20, 0x1df1, s70
	s_max_i32 s20, s20, 0
	s_lshr_b32 s38, s20, 6
	s_lshl_b32 s22, s24, 1
	v_readlane_b32 s20, v231, 26
	s_add_u32 s20, s20, s22
	v_readlane_b32 s21, v231, 27
	s_addc_u32 s21, s21, 0
	v_readlane_b32 s28, v231, 28
	v_readlane_b32 s29, v231, 29
	s_add_u32 s22, s28, s22
	s_addc_u32 s23, s29, 0
	s_lshl_b64 s[28:29], s[38:39], 13
	s_add_u32 s30, s20, s28
	s_addc_u32 s31, s21, s29
	s_add_u32 s28, s22, s28
	s_addc_u32 s29, s23, s29
	global_load_dwordx4 v[82:85], v134, s[30:31]
	global_load_dwordx4 v[86:89], v134, s[28:29]
	global_load_dwordx4 v[90:93], v135, s[30:31]
	global_load_dwordx4 v[94:97], v135, s[28:29]
	v_add_u32_e32 v46, s96, v132
	v_mov_b32_e32 v47, 0
	v_lshlrev_b64 v[46:47], 11, v[46:47]
	v_lshl_add_u64 v[46:47], s[42:43], 0, v[46:47]
	v_or_b32_e32 v48, s95, v102
	v_lshlrev_b32_e32 v48, 7, v48
	v_mov_b32_e32 v49, 0
	v_lshl_add_u64 v[46:47], v[46:47], 0, v[48:49]
	v_lshl_add_u64 v[46:47], v[46:47], 0, v[122:123]
	global_load_dwordx4 v[66:69], v[46:47], off offset:32
	global_load_dwordx4 v[70:73], v[46:47], off offset:64
	global_load_dwordx4 v[74:77], v[46:47], off offset:96
	global_load_dwordx4 v[78:81], v[46:47], off
	v_mbcnt_lo_u32_b32 v40, -1, 0
	v_mbcnt_hi_u32_b32 v40, -1, v40
	v_xor_b32_e32 v41, 16, v40
	v_lshlrev_b32_e32 v41, 2, v41
	v_xor_b32_e32 v42, 32, v40
	v_lshlrev_b32_e32 v42, 2, v42
	ds_bpermute_b32 v43, v41, v129
	ds_bpermute_b32 v44, v41, v235
	s_waitcnt lgkmcnt(0)
	v_add_f32_e32 v129, v129, v43
	v_add_f32_e32 v235, v235, v44
	s_nop 0
	ds_bpermute_b32 v43, v42, v129
	ds_bpermute_b32 v44, v42, v235
	s_waitcnt lgkmcnt(0)
	v_add_f32_e32 v129, v129, v43
	v_add_f32_e32 v235, v235, v44
	v_div_scale_f32 v40, s[98:99], v129, v129, v149
	v_rcp_f32_e32 v41, v40
	v_div_scale_f32 v42, vcc, v149, v129, v149
	v_fma_f32 v43, -v40, v41, 1.0
	v_fmac_f32_e32 v41, v43, v41
	v_mul_f32_e32 v43, v42, v41
	v_fma_f32 v38, -v40, v43, v42
	v_fmac_f32_e32 v43, v38, v41
	v_fma_f32 v40, -v40, v43, v42
	v_div_fmas_f32 v40, v40, v41, v43
	v_div_fixup_f32 v38, v40, v129, v149
	v_div_scale_f32 v40, s[98:99], v235, v235, v147
	v_rcp_f32_e32 v41, v40
	v_div_scale_f32 v42, vcc, v147, v235, v147
	v_fma_f32 v43, -v40, v41, 1.0
	v_fmac_f32_e32 v41, v43, v41
	v_mul_f32_e32 v43, v42, v41
	v_fma_f32 v44, -v40, v43, v42
	v_fmac_f32_e32 v43, v44, v41
	v_fma_f32 v40, -v40, v43, v42
	v_div_fmas_f32 v40, v40, v41, v43
	v_div_fixup_f32 v44, v40, v235, v147
	ds_read2_b32 v[50:51], v237 offset0:0 offset1:1
	ds_read2_b32 v[52:53], v237 offset0:2 offset1:3
	ds_read2_b32 v[54:55], v237 offset0:16 offset1:17
	ds_read2_b32 v[56:57], v237 offset0:18 offset1:19
	ds_read2_b32 v[58:59], v237 offset0:32 offset1:33
	ds_read2_b32 v[60:61], v237 offset0:34 offset1:35
	ds_read2_b32 v[62:63], v237 offset0:48 offset1:49
	ds_read2_b32 v[64:65], v237 offset0:50 offset1:51
	s_waitcnt lgkmcnt(7)
	v_pk_fma_f32 v[50:51], v[2:3], v[38:39], v[50:51] op_sel_hi:[1,0,1]
	s_waitcnt lgkmcnt(6)
	v_pk_fma_f32 v[52:53], v[4:5], v[38:39], v[52:53] op_sel_hi:[1,0,1]
	s_waitcnt lgkmcnt(5)
	v_pk_fma_f32 v[54:55], v[6:7], v[38:39], v[54:55] op_sel_hi:[1,0,1]
	s_waitcnt lgkmcnt(4)
	v_pk_fma_f32 v[56:57], v[8:9], v[38:39], v[56:57] op_sel_hi:[1,0,1]
	s_waitcnt lgkmcnt(3)
	v_pk_fma_f32 v[58:59], v[10:11], v[38:39], v[58:59] op_sel_hi:[1,0,1]
	s_waitcnt lgkmcnt(2)
	v_pk_fma_f32 v[60:61], v[12:13], v[38:39], v[60:61] op_sel_hi:[1,0,1]
	s_waitcnt lgkmcnt(1)
	v_pk_fma_f32 v[62:63], v[14:15], v[38:39], v[62:63] op_sel_hi:[1,0,1]
	s_waitcnt lgkmcnt(0)
	v_pk_fma_f32 v[64:65], v[16:17], v[38:39], v[64:65] op_sel_hi:[1,0,1]
	ds_write2_b32 v237, v50, v51 offset0:0 offset1:1
	ds_write2_b32 v237, v52, v53 offset0:2 offset1:3
	ds_write2_b32 v237, v54, v55 offset0:16 offset1:17
	ds_write2_b32 v237, v56, v57 offset0:18 offset1:19
	ds_write2_b32 v237, v58, v59 offset0:32 offset1:33
	ds_write2_b32 v237, v60, v61 offset0:34 offset1:35
	ds_write2_b32 v237, v62, v63 offset0:48 offset1:49
	ds_write2_b32 v237, v64, v65 offset0:50 offset1:51
	ds_read2_b32 v[50:51], v238 offset0:0 offset1:1
	ds_read2_b32 v[52:53], v238 offset0:2 offset1:3
	ds_read2_b32 v[54:55], v238 offset0:16 offset1:17
	ds_read2_b32 v[56:57], v238 offset0:18 offset1:19
	ds_read2_b32 v[58:59], v238 offset0:32 offset1:33
	ds_read2_b32 v[60:61], v238 offset0:34 offset1:35
	ds_read2_b32 v[62:63], v238 offset0:48 offset1:49
	ds_read2_b32 v[64:65], v238 offset0:50 offset1:51
	s_waitcnt lgkmcnt(7)
	v_pk_fma_f32 v[50:51], v[18:19], v[44:45], v[50:51] op_sel_hi:[1,0,1]
	s_waitcnt lgkmcnt(6)
	v_pk_fma_f32 v[52:53], v[20:21], v[44:45], v[52:53] op_sel_hi:[1,0,1]
	s_waitcnt lgkmcnt(5)
	v_pk_fma_f32 v[54:55], v[22:23], v[44:45], v[54:55] op_sel_hi:[1,0,1]
	s_waitcnt lgkmcnt(4)
	v_pk_fma_f32 v[56:57], v[24:25], v[44:45], v[56:57] op_sel_hi:[1,0,1]
	s_waitcnt lgkmcnt(3)
	v_pk_fma_f32 v[58:59], v[26:27], v[44:45], v[58:59] op_sel_hi:[1,0,1]
	s_waitcnt lgkmcnt(2)
	v_pk_fma_f32 v[60:61], v[28:29], v[44:45], v[60:61] op_sel_hi:[1,0,1]
	s_waitcnt lgkmcnt(1)
	v_pk_fma_f32 v[62:63], v[30:31], v[44:45], v[62:63] op_sel_hi:[1,0,1]
	s_waitcnt lgkmcnt(0)
	v_pk_fma_f32 v[64:65], v[32:33], v[44:45], v[64:65] op_sel_hi:[1,0,1]
	ds_write2_b32 v238, v50, v51 offset0:0 offset1:1
	ds_write2_b32 v238, v52, v53 offset0:2 offset1:3
	ds_write2_b32 v238, v54, v55 offset0:16 offset1:17
	ds_write2_b32 v238, v56, v57 offset0:18 offset1:19
	ds_write2_b32 v238, v58, v59 offset0:32 offset1:33
	ds_write2_b32 v238, v60, v61 offset0:34 offset1:35
	ds_write2_b32 v238, v62, v63 offset0:48 offset1:49
	ds_write2_b32 v238, v64, v65 offset0:50 offset1:51
	s_sub_i32 s25, s72, s38
	v_mov_b32_e32 v34, 0
	v_mov_b32_e32 v35, 0
	v_mov_b32_e32 v36, 0
	v_mov_b32_e32 v37, 0
	v_mov_b32_e32 v38, 0
	v_mov_b32_e32 v39, 0
	v_mov_b32_e32 v40, 0
	v_mov_b32_e32 v41, 0
	v_mov_b32_e32 v42, 0
	v_mov_b32_e32 v43, 0
	v_mov_b32_e32 v44, 0
	v_mov_b32_e32 v45, 0
	v_mov_b32_e32 v46, 0
	v_mov_b32_e32 v47, 0
	v_mov_b32_e32 v48, 0
	v_mov_b32_e32 v49, 0
	v_mov_b32_e32 v50, 0
	v_mov_b32_e32 v51, 0
	v_mov_b32_e32 v52, 0
	v_mov_b32_e32 v53, 0
	v_mov_b32_e32 v54, 0
	v_mov_b32_e32 v55, 0
	v_mov_b32_e32 v56, 0
	v_mov_b32_e32 v57, 0
	v_mov_b32_e32 v58, 0
	v_mov_b32_e32 v59, 0
	v_mov_b32_e32 v60, 0
	v_mov_b32_e32 v61, 0
	v_mov_b32_e32 v62, 0
	v_mov_b32_e32 v63, 0
	v_mov_b32_e32 v64, 0
	v_mov_b32_e32 v65, 0
	v_mov_b32_e32 v129, 0
	s_cmp_lt_i32 s25, 0
	s_cbranch_scc1 .LBB0_2196
	s_cmp_eq_u32 s72, s38
	s_waitcnt vmcnt(0)
	ds_write_b128 v153, v[82:85]
	ds_write_b128 v153, v[86:89] offset:9216
	ds_write_b128 v155, v[90:93]
	ds_write_b128 v155, v[94:97] offset:9216
	s_cbranch_scc1 .LBB0_2185
	s_branch .Lsb16_w2184
